# NSA selected branch: double-buffered K/V LDS staging (second image in free LDS), one workgroup barrier per 64-key block instead of two
# baseline (speedup 1.0000x reference)
;   __device__ __forceinline__ half_t* vsT() const { return (half_t*)(ws() + OFF_vsT); }
; template <bool ONLINE, bool HASV, bool WANTP, class PRE, class FU, class VF, class PO> ...
;   half_t* Ks = (half_t*)smem;
;   half_t* Vs = Ks + 64 * 72;
;   const int lane = tid & 63;
;   StageRegs sr;
;   load_stage<HASV>(sr, Kb, ldk, VT, ldv, blk_lo * 64, tid);
;   for (int blk = blk_lo; blk <= blk_hi; ++blk) {
;     __syncthreads();
;     write_stage<HASV>(sr, Ks, Vs, tid);
;     __syncthreads();
;     const int nb = blk < blk_hi ? blk + 1 : blk;
;     load_stage<HASV>(sr, Kb, ldk, VT, ldv, nb * 64, tid);
; __device__ __forceinline__ void nsa_item(const KP& p, int b, int g, int tile, char* smem) {
;     ...
;   {
;     const half_t* Ksel = ub + C_CKS + g * 64;
;     const half_t* Vsel = p.vsT() + (size_t)(b * 2 + g) * 64 * SEQ;
;     auto pre = [&](int blk) __attribute__((always_inline)) {
;       const unsigned long long mm_ = (blk < 64) ? mylo : myhi;
;       return (int)((mm_ >> (blk & 63)) & 1ull);
;     };
;     auto vfn = [&](int key, int flag) __attribute__((always_inline)) { return flag != 0 && key <= tj; };
;     ds_reset(st);
;     auto fulls = [&](int blk) __attribute__((always_inline)) { return blk * 64 + 63 <= tw0; };
;     run_dense<true, true, false>(st, Ksel, NU, Vsel, SEQ, 0, (t0 + 31) >> 6, qf, pre, fulls, vfn, 0.f, 0.f, nopost, smem, tid);
.LBB0_1646:
	v_mov_b64_e32 v[4:5], s[52:53]
	v_mad_i64_i32 v[6:7], s[2:3], v188, s5, v[4:5]
	v_mad_i64_i32 v[4:5], s[2:3], v84, s5, v[4:5]
	v_lshl_add_u64 v[6:7], v[6:7], 0, v[0:1]
	v_lshl_add_u64 v[4:5], v[4:5], 0, v[0:1]
	v_lshlrev_b64 v[14:15], 14, v[188:189]
	global_load_dwordx4 v[6:9], v[6:7], off
	s_nop 0
	global_load_dwordx4 v[10:13], v[4:5], off
	v_lshl_add_u64 v[4:5], s[54:55], 0, v[14:15]
	v_lshlrev_b64 v[120:121], 14, v[84:85]
	v_lshl_add_u64 v[122:123], v[4:5], 0, v[0:1]
	v_lshl_add_u64 v[4:5], s[54:55], 0, v[120:121]
	v_lshl_add_u64 v[124:125], v[4:5], 0, v[0:1]
	global_load_dwordx4 v[116:119], v[122:123], off
	global_load_dwordx4 v[112:115], v[124:125], off
	v_lshl_add_u32 v2, v100, 4, v2
	ds_read_b128 v[2:5], v2 offset:51712
	v_mov_b32_e32 v46, v1
	v_mov_b32_e32 v47, v1
	v_mov_b32_e32 v32, v1
	v_mov_b32_e32 v33, v1
	v_mov_b32_e32 v34, v1
	v_mov_b32_e32 v35, v1
	v_mov_b32_e32 v36, v1
	v_mov_b32_e32 v37, v1
	v_mov_b32_e32 v38, v1
	v_mov_b32_e32 v39, v1
	v_mov_b32_e32 v40, v1
	v_mov_b32_e32 v41, v1
	v_mov_b32_e32 v42, v1
	v_mov_b32_e32 v43, v1
	v_mov_b32_e32 v44, v1
	v_mov_b32_e32 v45, v1
	v_mov_b64_e32 v[94:95], v[46:47]
	s_lshr_b32 s2, s31, 6
	v_lshl_add_u64 v[126:127], s[52:53], 0, v[0:1]
	s_mov_b32 s3, 0
	v_mov_b32_e32 v128, 0xc61c4000
	v_mov_b32_e32 v189, 0
	s_mov_b32 s14, 63
	v_mov_b64_e32 v[92:93], v[44:45]
	v_mov_b64_e32 v[90:91], v[42:43]
	v_mov_b64_e32 v[88:89], v[40:41]
	v_mov_b64_e32 v[86:87], v[38:39]
	v_mov_b64_e32 v[84:85], v[36:37]
	v_mov_b64_e32 v[82:83], v[34:35]
	v_mov_b64_e32 v[80:81], v[32:33]
	s_movk_i32 s69, 0x4800
	s_min_u32 s8, s2, 1
	s_lshl_b32 s8, s8, 6
	s_waitcnt lgkmcnt(0)
	s_barrier
	s_waitcnt vmcnt(3)
	ds_write_b128 v199, v[6:9]
	s_waitcnt vmcnt(2)
	ds_write_b128 v199, v[10:13] offset:4608
	s_waitcnt vmcnt(1)
	ds_write2_b64 v209, v[116:117], v[118:119] offset0:128 offset1:130
	s_waitcnt vmcnt(0)
	ds_write2_b64 v210, v[112:113], v[114:115] offset0:192 offset1:194
	v_add_u32_e32 v8, s8, v188
	v_mad_i64_i32 v[6:7], s[38:39], v8, s5, v[126:127]
	v_add_u32_e32 v8, 32, v8
	v_mad_i64_i32 v[10:11], s[38:39], v8, s5, v[126:127]
	s_lshl_b64 s[38:39], s[8:9], 1
	s_nop 0
	v_lshl_add_u64 v[64:65], v[122:123], 0, s[38:39]
	s_waitcnt lgkmcnt(0)
	s_barrier
	global_load_dwordx4 v[6:9], v[6:7], off
	s_nop 0
	global_load_dwordx4 v[10:13], v[10:11], off
	v_lshl_add_u64 v[66:67], v[124:125], 0, s[38:39]
	global_load_dwordx4 v[116:119], v[64:65], off
	global_load_dwordx4 v[112:115], v[66:67], off
	s_mov_b32 s44, 0xd400
	s_mov_b32 s45, 0xffff2c00
	v_add_u32_e32 v199, 0xd400, v199
	v_add_u32_e32 v209, 0xd400, v209
	v_add_u32_e32 v210, 0xd400, v210
; template <bool ONLINE, bool HASV, bool FAST, class VF> ...
;     ...
;   f32x16 s[2];
; #pragma unroll
;   for (int kt = 0; kt < 2; ++kt) {
; #pragma unroll
;     for (int r = 0; r < 16; ++r) s[kt][r] = 0.f;
; #pragma unroll
;     for (int ks = 0; ks < 4; ++ks) {
;       const h8 a = *(const h8*)&Ks[(32 * kt + c) * 72 + 16 * ks + 8 * h];
;       s[kt] = __builtin_amdgcn_mfma_f32_32x32x16_f16(a, qf[ks], s[kt], 0, 0, 0);
;     }
;   }
;   float cm = NEGF;
; #pragma unroll
;   for (int kt = 0; kt < 2; ++kt)
; #pragma unroll
;     for (int r = 0; r < 16; ++r) {
;       const int key = key0 + 32 * kt + (r & 3) + 8 * (r >> 2) + 4 * h;
;       const float v = (FAST ? (flag != 0) : valid(key, flag)) ? s[kt][r] : NEGF;
;       s[kt][r] = v;
;       cm = fmaxf(cm, v);
;     }
;   float mnew;
;   if (ONLINE) {
;     cm = fmaxf(cm, __shfl_xor(cm, 32));
;     mnew = st.m;
;     if (__ballot(cm > st.m + 8.0f) != 0ull) {
;       mnew = fmaxf(st.m, cm);
;       const float alpha = __builtin_amdgcn_exp2f(st.m - mnew);
;       st.m = mnew;
;       st.l *= alpha;
;       if (HASV) {
; #pragma unroll
;         for (int dt = 0; dt < 2; ++dt)
; #pragma unroll
;           for (int r = 0; r < 16; ++r) st.o[dt][r] *= alpha;
;       }
;     }
; template <bool ONLINE, bool HASV, bool WANTP, class PRE, class FU, class VF, class PO> ...
;     ...
;     const int flag = pre(blk);
;     if (__ballot(flag != 0) != 0ull) {
;       f32x16 pp[2];
;       if (full(blk))
.LBB0_1647:
	s_add_i32 s15, s3, 1
	s_cmp_lt_u32 s3, 64
	s_cselect_b64 vcc, -1, 0
	v_cndmask_b32_e32 v65, v5, v3, vcc
	v_cndmask_b32_e32 v64, v4, v2, vcc
	v_lshrrev_b64 v[64:65], s3, v[64:65]
	v_and_b32_e32 v130, 1, v64
	v_cmp_ne_u32_e32 vcc, 0, v130
	s_cbranch_vccz .LBB0_1657
	v_cmp_le_i32_e32 vcc, s14, v190
	v_add_f32_e32 v129, 0x41000000, v128
	s_and_saveexec_b64 s[38:39], vcc
	s_xor_b64 s[38:39], exec, s[38:39]
	s_cbranch_execz .LBB0_1652
	ds_read_b128 v[64:67], v200
	ds_read_b128 v[68:71], v200 offset:32
	v_cmp_eq_u32_e32 vcc, 0, v130
	s_waitcnt lgkmcnt(1)
	v_mfma_f32_32x32x16_f16 v[96:111], v[64:67], v[148:151], 0
	ds_read_b128 v[64:67], v200 offset:64
	s_waitcnt lgkmcnt(1)
	v_mfma_f32_32x32x16_f16 v[96:111], v[68:71], v[152:155], v[96:111]
	s_waitcnt lgkmcnt(0)
	v_mfma_f32_32x32x16_f16 v[96:111], v[64:67], v[156:159], v[96:111]
	ds_read_b128 v[64:67], v200 offset:96
	s_waitcnt lgkmcnt(0)
	v_mfma_f32_32x32x16_f16 v[96:111], v[64:67], v[144:147], v[96:111]
	ds_read_b128 v[64:67], v201
	ds_read_b128 v[132:135], v201 offset:32
	s_waitcnt lgkmcnt(1)
	v_mfma_f32_32x32x16_f16 v[64:79], v[64:67], v[148:151], 0
	s_nop 7
	v_cndmask_b32_e32 v141, v96, v242, vcc
	v_cndmask_b32_e32 v138, v97, v242, vcc
	v_max3_f32 v96, v141, s74, v138
	v_cndmask_b32_e32 v139, v98, v242, vcc
	v_cndmask_b32_e32 v137, v99, v242, vcc
	v_max3_f32 v96, v96, v139, v137
	v_cndmask_b32_e32 v140, v103, v242, vcc
	s_waitcnt lgkmcnt(0)
	v_mfma_f32_32x32x16_f16 v[64:79], v[132:135], v[152:155], v[64:79]
	ds_read_b128 v[132:135], v201 offset:64
	v_cndmask_b32_e32 v136, v104, v242, vcc
	v_cndmask_b32_e32 v131, v106, v242, vcc
	v_cndmask_b32_e32 v130, v107, v242, vcc
	v_cndmask_b32_e32 v107, v108, v242, vcc
	v_cndmask_b32_e32 v106, v109, v242, vcc
	v_cndmask_b32_e32 v104, v111, v242, vcc
	s_waitcnt lgkmcnt(0)
	v_mfma_f32_32x32x16_f16 v[64:79], v[132:135], v[156:159], v[64:79]
	ds_read_b128 v[132:135], v201 offset:96
	s_waitcnt lgkmcnt(0)
	v_mfma_f32_32x32x16_f16 v[64:79], v[132:135], v[144:147], v[64:79]
	v_cndmask_b32_e32 v135, v100, v242, vcc
	v_cndmask_b32_e32 v132, v101, v242, vcc
	v_max3_f32 v96, v96, v135, v132
	v_cndmask_b32_e32 v134, v102, v242, vcc
	v_max3_f32 v96, v96, v134, v140
	v_cndmask_b32_e32 v133, v105, v242, vcc
	v_max3_f32 v96, v96, v136, v133
	v_max3_f32 v96, v96, v131, v130
	v_max3_f32 v96, v96, v107, v106
	v_cndmask_b32_e32 v105, v110, v242, vcc
	v_max3_f32 v96, v96, v105, v104
	s_nop 0
	v_cndmask_b32_e32 v103, v64, v242, vcc
	v_cndmask_b32_e32 v102, v65, v242, vcc
	v_max3_f32 v64, v96, v103, v102
	v_cndmask_b32_e32 v101, v66, v242, vcc
	v_cndmask_b32_e32 v100, v67, v242, vcc
	v_max3_f32 v64, v64, v101, v100
	v_cndmask_b32_e32 v99, v68, v242, vcc
	v_cndmask_b32_e32 v98, v69, v242, vcc
	v_max3_f32 v64, v64, v99, v98
	v_cndmask_b32_e32 v97, v70, v242, vcc
	v_cndmask_b32_e32 v96, v71, v242, vcc
	v_max3_f32 v64, v64, v97, v96
	v_cndmask_b32_e32 v71, v72, v242, vcc
	v_cndmask_b32_e32 v69, v73, v242, vcc
	v_max3_f32 v64, v64, v71, v69
	v_cndmask_b32_e32 v70, v74, v242, vcc
	v_cndmask_b32_e32 v68, v75, v242, vcc
	v_max3_f32 v64, v64, v70, v68
	v_cndmask_b32_e32 v67, v76, v242, vcc
	v_cndmask_b32_e32 v65, v77, v242, vcc
	v_max3_f32 v72, v64, v67, v65
	v_cndmask_b32_e32 v66, v78, v242, vcc
	v_cndmask_b32_e32 v64, v79, v242, vcc
	v_max3_f32 v72, v72, v66, v64
	ds_bpermute_b32 v73, v204, v72
	s_waitcnt lgkmcnt(0)
	v_max_f32_e32 v73, v73, v73
	v_max_f32_e32 v72, v72, v73
	v_cmp_gt_f32_e32 vcc, v72, v129
	s_cbranch_vccz .LBB0_1651
	v_max_f32_e32 v72, v72, v72
	v_max_f32_e32 v73, v128, v128
	v_max_f32_e32 v73, v73, v72
	v_sub_f32_e32 v72, v128, v73
	v_exp_f32_e32 v72, v72
	v_mov_b32_e32 v128, v73
	v_mul_f32_e32 v189, v189, v72
	v_pk_mul_f32 v[94:95], v[94:95], v[72:73] op_sel_hi:[1,0]
	v_pk_mul_f32 v[92:93], v[92:93], v[72:73] op_sel_hi:[1,0]
	v_pk_mul_f32 v[90:91], v[90:91], v[72:73] op_sel_hi:[1,0]
	v_pk_mul_f32 v[88:89], v[88:89], v[72:73] op_sel_hi:[1,0]
	v_pk_mul_f32 v[86:87], v[86:87], v[72:73] op_sel_hi:[1,0]
	v_pk_mul_f32 v[84:85], v[84:85], v[72:73] op_sel_hi:[1,0]
	v_pk_mul_f32 v[82:83], v[82:83], v[72:73] op_sel_hi:[1,0]
	v_pk_mul_f32 v[80:81], v[80:81], v[72:73] op_sel_hi:[1,0]
	v_pk_mul_f32 v[46:47], v[46:47], v[72:73] op_sel_hi:[1,0]
	v_pk_mul_f32 v[44:45], v[44:45], v[72:73] op_sel_hi:[1,0]
	v_pk_mul_f32 v[42:43], v[42:43], v[72:73] op_sel_hi:[1,0]
	v_pk_mul_f32 v[40:41], v[40:41], v[72:73] op_sel_hi:[1,0]
	v_pk_mul_f32 v[38:39], v[38:39], v[72:73] op_sel_hi:[1,0]
	v_pk_mul_f32 v[36:37], v[36:37], v[72:73] op_sel_hi:[1,0]
	v_pk_mul_f32 v[34:35], v[34:35], v[72:73] op_sel_hi:[1,0]
	v_pk_mul_f32 v[32:33], v[32:33], v[72:73] op_sel_hi:[1,0]

;   __device__ __forceinline__ half_t* vwT() const { return (half_t*)(ws() + OFF_vwT); }
; template <bool ONLINE, bool HASV, bool WANTP, class PRE, class FU, class VF, class PO> ...
;     ...
;   for (int blk = blk_lo; blk <= blk_hi; ++blk) {
;     __syncthreads();
;     write_stage<HASV>(sr, Ks, Vs, tid);
;     __syncthreads();
;     const int nb = blk < blk_hi ? blk + 1 : blk;
;     load_stage<HASV>(sr, Kb, ldk, VT, ldv, nb * 64, tid);
;     const int flag = pre(blk);
;     if (__ballot(flag != 0) != 0ull) {
;       f32x16 pp[2];
;       if (full(blk))
;         dense_block<ONLINE, HASV, true>(st, Ks, Vs, qf, blk * 64, flag, valid, fixed_m, fixed_invl,
;                                         WANTP ? pp : (f32x16*)nullptr, lane);
;       else
;         dense_block<ONLINE, HASV, false>(st, Ks, Vs, qf, blk * 64, flag, valid, fixed_m, fixed_invl,
;                                          WANTP ? pp : (f32x16*)nullptr, lane);
;       if (WANTP) post(blk * 64, pp);
;     }
;   }
; __device__ __forceinline__ void nsa_item(const KP& p, int b, int g, int tile, char* smem) {
;     ...
;     float lt = st.l;
;     lt += __shfl_xor(lt, 32);
;     const float sc = lt > 0.f ? gate[1] / lt : 0.f;
; #pragma unroll
;     for (int dt = 0; dt < 2; ++dt)
; #pragma unroll
;       for (int r = 0; r < 16; ++r) res[dt][r] += sc * st.o[dt][r];
;   }
;   {
;     const half_t* Kw = ub + C_CKW + g * 64;
;     const half_t* Vw = p.vwT() + (size_t)(b * 2 + g) * 64 * SEQ;
;     auto pre = [&](int blk) __attribute__((always_inline)) {
;       return (int)((blk * 64 <= tj) && (blk * 64 + 63 > tj - 512));
;     };
;     auto vfn = [&](int key, int) __attribute__((always_inline)) { return key <= tj && key > tj - 512; };
;     ds_reset(st);
;     auto fullw = [&](int blk) __attribute__((always_inline)) { return blk * 64 + 63 <= tw0 && blk * 64 > tw0 + 7 - 512; };
;     run_dense<true, true, false>(st, Kw, NU, Vw, SEQ, max(0, t0 - 511) >> 6, (t0 + 31) >> 6, qf, pre, fullw, vfn, 0.f, 0.f,
;                                  nopost, smem, tid);
.LBB0_1657:
	s_waitcnt vmcnt(3)
	ds_write_b128 v199, v[6:9]
	s_waitcnt vmcnt(2)
	ds_write_b128 v199, v[10:13] offset:4608
	s_waitcnt vmcnt(1)
	ds_write2_b64 v209, v[116:117], v[118:119] offset0:128 offset1:130
	s_waitcnt vmcnt(0)
	ds_write2_b64 v210, v[112:113], v[114:115] offset0:192 offset1:194
	s_add_i32 s8, s3, 2
	s_min_u32 s8, s8, s2
	s_lshl_b32 s8, s8, 6
	v_add_u32_e32 v8, s8, v188
	v_mad_i64_i32 v[6:7], s[38:39], v8, s5, v[126:127]
	v_add_u32_e32 v8, 32, v8
	v_mad_i64_i32 v[10:11], s[38:39], v8, s5, v[126:127]
	s_lshl_b64 s[38:39], s[8:9], 1
	s_nop 0
	v_lshl_add_u64 v[64:65], v[122:123], 0, s[38:39]
	global_load_dwordx4 v[6:9], v[6:7], off
	s_nop 0
	global_load_dwordx4 v[10:13], v[10:11], off
	v_lshl_add_u64 v[66:67], v[124:125], 0, s[38:39]
	global_load_dwordx4 v[116:119], v[64:65], off
	global_load_dwordx4 v[112:115], v[66:67], off
	v_add_u32_e32 v200, s44, v200
	v_add_u32_e32 v201, s44, v201
	v_add_u32_e32 v202, s44, v202
	v_add_u32_e32 v203, s44, v203
	v_add_u32_e32 v205, s44, v205
	v_add_u32_e32 v206, s44, v206
	v_add_u32_e32 v207, s44, v207
	v_add_u32_e32 v208, s44, v208
	v_add_u32_e32 v199, s45, v199
	v_add_u32_e32 v209, s45, v209
	v_add_u32_e32 v210, s45, v210
	s_sub_i32 s44, 0, s44
	s_sub_i32 s45, 0, s45
	s_waitcnt lgkmcnt(0)
	s_barrier
	s_add_i32 s14, s14, 64
	s_cmp_lg_u32 s3, s2
	s_cbranch_scc0 .Lnsa_sel_exit
	s_mov_b32 s3, s15
	s_branch .LBB0_1647
.Lnsa_sel_exit:
	s_cmp_lt_i32 s44, 0
	s_cbranch_scc0 .Lnsa_sel_x1
	v_add_u32_e32 v200, s44, v200
	v_add_u32_e32 v201, s44, v201
	v_add_u32_e32 v202, s44, v202
	v_add_u32_e32 v203, s44, v203
	v_add_u32_e32 v205, s44, v205
	v_add_u32_e32 v206, s44, v206
	v_add_u32_e32 v207, s44, v207
	v_add_u32_e32 v208, s44, v208
.Lnsa_sel_x1:
	s_cmp_lt_i32 s45, 0
	s_cbranch_scc0 .Lnsa_sel_x2
	v_add_u32_e32 v199, s45, v199
	v_add_u32_e32 v209, s45, v209
	v_add_u32_e32 v210, s45, v210
.Lnsa_sel_x2:
.LBB0_1659:
	ds_bpermute_b32 v187, v204, v189
	s_max_i32 s8, s31, 0x1ff
	s_addk_i32 s8, 0xfe01
	s_lshr_b32 s3, s8, 6
	s_cmp_le_u32 s3, s2
	s_cbranch_scc0 .LBB0_1590
	s_andn2_b32 s8, s8, 63
	v_lshl_add_u64 v[2:3], s[60:61], 0, v[14:15]
	v_lshl_add_u64 v[4:5], s[60:61], 0, v[120:121]
	s_lshl_b64 s[14:15], s[8:9], 1
	s_waitcnt vmcnt(3)
	v_lshl_add_u64 v[6:7], v[4:5], 0, s[14:15]
	v_lshl_add_u64 v[8:9], v[2:3], 0, s[14:15]
	v_lshl_add_u64 v[6:7], v[6:7], 0, v[0:1]
	v_lshl_add_u64 v[8:9], v[8:9], 0, v[0:1]
	s_waitcnt vmcnt(2)
	v_add_u32_e32 v10, s8, v188
	global_load_dwordx4 v[160:163], v[6:7], off
	global_load_dwordx4 v[164:167], v[8:9], off
	v_add_u32_e32 v8, 32, v10
	v_mov_b64_e32 v[6:7], s[56:57]
	v_mad_i64_i32 v[8:9], s[14:15], v8, s5, v[6:7]
	v_lshl_add_u64 v[8:9], v[8:9], 0, v[0:1]
	v_mad_i64_i32 v[6:7], s[14:15], v10, s5, v[6:7]
	v_lshl_add_u64 v[6:7], v[6:7], 0, v[0:1]
	global_load_dwordx4 v[168:171], v[8:9], off
	global_load_dwordx4 v[172:175], v[6:7], off
	s_lshl_b32 s8, s30, 6
	s_or_b32 s8, s91, s8
	s_andn2_b32 s8, s8, 31
	s_sub_i32 s8, 0x1fe0, s8
	s_max_i32 s8, s8, 0x1ff
	v_mov_b32_e32 v14, v1
	v_mov_b32_e32 v15, v1
	v_lshl_add_u64 v[192:193], s[56:57], 0, v[0:1]
	v_lshl_add_u64 v[194:195], v[2:3], 0, v[0:1]
	v_lshl_add_u64 v[196:197], v[4:5], 0, v[0:1]
	s_addk_i32 s8, 0xfe01
	v_mov_b32_e32 v0, v1
	v_mov_b32_e32 v2, v1
	v_mov_b32_e32 v3, v1
	v_mov_b32_e32 v4, v1
	v_mov_b32_e32 v5, v1
	v_mov_b32_e32 v6, v1
	v_mov_b32_e32 v7, v1
	v_mov_b32_e32 v8, v1
	v_mov_b32_e32 v9, v1
	v_mov_b32_e32 v10, v1
	v_mov_b32_e32 v11, v1
	v_mov_b32_e32 v12, v1
	v_mov_b32_e32 v13, v1
	v_mov_b64_e32 v[78:79], v[14:15]
	v_mov_b64_e32 v[110:111], v[14:15]
	v_add_u32_e32 v211, 0xfffffe00, v181
	v_add_u32_e32 v212, 0xfffffe07, v190
	s_and_b32 s14, s8, 0xffffffc0
	v_mov_b32_e32 v213, 0xc61c4000
	v_mov_b32_e32 v191, 0
	v_mov_b64_e32 v[76:77], v[12:13]
	v_mov_b64_e32 v[74:75], v[10:11]
	v_mov_b64_e32 v[72:73], v[8:9]
	v_mov_b64_e32 v[70:71], v[6:7]
	v_mov_b64_e32 v[68:69], v[4:5]
	v_mov_b64_e32 v[66:67], v[2:3]
	v_mov_b64_e32 v[64:65], v[0:1]
	v_mov_b64_e32 v[108:109], v[12:13]
	v_mov_b64_e32 v[106:107], v[10:11]
	v_mov_b64_e32 v[104:105], v[8:9]
	v_mov_b64_e32 v[102:103], v[6:7]
	v_mov_b64_e32 v[100:101], v[4:5]
	v_mov_b64_e32 v[98:99], v[2:3]
	v_mov_b64_e32 v[96:97], v[0:1]
	s_branch .LBB0_1664
